# attention selected loop: next step block-mask word prefetched one step ahead into spare VGPRs (no exposed ds_read at step start); K/V prefetch waited where consumed instead of at loop top
# speedup vs baseline: 1.0221x; 1.0019x over previous
.LBB0_1455:
	s_cmp_lt_i32 s18, 0
	s_cbranch_scc1 .LBB0_1484
	s_and_b64 s[0:1], s[16:17], exec
	v_readlane_b32 s23, v240, 47
	s_cselect_b32 s9, s23, 0
	s_add_i32 s21, 0, 0x2800
	s_add_i32 s22, 0, 0x7800
	s_and_b64 s[0:1], s[16:17], exec
	s_cselect_b32 s0, s22, s21
	v_add3_u32 v112, s0, v163, v166
	s_cselect_b32 s1, s21, s22
	s_cselect_b32 s16, 0, s23
	s_waitcnt vmcnt(0)
	v_add_u32_e32 v70, s0, v97
	s_add_u32 s0, s24, s8
	v_add_u32_e32 v66, s9, v150
	v_add_u32_e32 v67, s1, v97
	v_add_u32_e32 v68, s16, v97
	v_add_u32_e32 v69, s16, v150
	v_add3_u32 v113, s1, v163, v166
	v_add_u32_e32 v71, s9, v97
	s_addc_u32 s1, s25, 0
	v_sub_u32_e32 v111, v160, v158
	v_lshl_add_u64 v[106:107], s[0:1], 0, v[164:165]
	v_add_u32_e32 v114, v66, v171
	v_add_u32_e32 v115, v68, v96
	v_add_u32_e32 v116, v67, v96
	v_add_u32_e32 v117, v69, v171
	v_add_u32_e32 v118, v71, v96
	v_add_u32_e32 v119, v70, v96
	s_max_i32 s98, s18, 0
	s_lshr_b32 s98, s98, 3
	s_and_b32 s98, s98, 0x1ffffffc
	v_add_u32_e32 v244, s98, v157
	ds_read_b32 v242, v244 offset:16
	s_waitcnt lgkmcnt(0)
	s_branch .LBB0_1459

.LBB0_1459:
	s_max_i32 s0, s19, 0
	s_lshl_b32 s76, s0, 6
	v_lshl_add_u64 v[66:67], v[152:153], 0, s[76:77]
	v_mad_u64_u32 v[70:71], s[0:1], v66, s33, v[106:107]
	v_mad_i32_i24 v71, v67, s33, v71
	global_load_dwordx4 v[66:69], v[70:71], off offset:1024
	s_nop 0
	global_load_dwordx4 v[70:73], v[70:71], off offset:1152
	s_max_i32 s98, s7, 0
	s_lshr_b32 s98, s98, 3
	s_and_b32 s98, s98, 0x1ffffffc
	v_add_u32_e32 v244, s98, v157
	ds_read_b32 v243, v244 offset:16
	s_and_b32 s16, s18, 31
	s_mov_b32 s9, s19
	v_lshrrev_b32_e32 v75, s18, v242
	v_and_b32_e32 v75, 1, v75
	v_bfe_u32 v74, v242, s16, 1
	v_cmp_eq_u32_e64 s[0:1], 1, v75
	v_cmp_ne_u32_e32 vcc, 0, v74
	s_cbranch_vccz .LBB0_1463
	ds_read_b128 v[120:123], v114
	ds_read_b128 v[124:127], v114 offset:2560
	ds_read_b128 v[128:131], v114 offset:5120
	ds_read_b128 v[132:135], v114 offset:7680
	ds_read_b128 v[136:139], v114 offset:64
	ds_read_b128 v[140:143], v114 offset:2624
	ds_read_b128 v[176:179], v114 offset:5184
	ds_read_b128 v[180:183], v114 offset:7744
	v_lshl_add_u32 v74, s18, 6, v111
	v_cvt_f32_i32_e32 v90, v74
	v_fma_f32 v74, v146, v90, -v109
	v_fma_f32 v90, v148, v90, -v110
	v_cndmask_b32_e64 v89, v173, v74, s[0:1]
	v_cndmask_b32_e64 v105, v173, v90, s[0:1]
	v_fma_f32 v74, v146, s77, v89
	v_fma_f32 v75, v146, s95, v89
	v_fma_f32 v76, v146, s4, v89
	v_fma_f32 v77, v146, s5, v89
	v_fma_f32 v78, v146, s86, v89
	v_fma_f32 v79, v146, s87, v89
	v_fma_f32 v80, v146, s84, v89
	v_fma_f32 v81, v146, s85, v89
	v_fma_f32 v82, v146, s88, v89
	v_fma_f32 v83, v146, s89, v89
	v_fma_f32 v84, v146, s90, v89
	v_fma_f32 v85, v146, s91, v89
	v_fma_f32 v86, v146, s72, v89
	v_fma_f32 v87, v146, s73, v89
	v_fma_f32 v88, v146, s74, v89
	v_fma_f32 v89, v146, s75, v89
	v_fma_f32 v90, v148, s77, v105
	v_fma_f32 v91, v148, s95, v105
	v_fma_f32 v92, v148, s4, v105
	v_fma_f32 v93, v148, s5, v105
	v_fma_f32 v94, v148, s86, v105
	v_fma_f32 v95, v148, s87, v105
	v_fma_f32 v96, v148, s84, v105
	v_fma_f32 v97, v148, s85, v105
	v_fma_f32 v98, v148, s88, v105
	v_fma_f32 v99, v148, s89, v105
	v_fma_f32 v100, v148, s90, v105
	v_fma_f32 v101, v148, s91, v105
	v_fma_f32 v102, v148, s72, v105
	v_fma_f32 v103, v148, s73, v105
	v_fma_f32 v104, v148, s74, v105
	v_fma_f32 v105, v148, s75, v105
	s_setprio 1
	s_waitcnt lgkmcnt(7)
	v_mfma_f32_16x16x32_bf16 v[74:77], v[120:123], v[6:9], v[74:77]
	v_mfma_f32_16x16x32_bf16 v[90:93], v[120:123], v[14:17], v[90:93]
	s_waitcnt lgkmcnt(6)
	v_mfma_f32_16x16x32_bf16 v[78:81], v[124:127], v[6:9], v[78:81]
	v_mfma_f32_16x16x32_bf16 v[94:97], v[124:127], v[14:17], v[94:97]
	s_waitcnt lgkmcnt(5)
	v_mfma_f32_16x16x32_bf16 v[120:123], v[128:131], v[6:9], v[82:85]
	v_mfma_f32_16x16x32_bf16 v[124:127], v[128:131], v[14:17], v[98:101]
	s_waitcnt lgkmcnt(4)
	v_mfma_f32_16x16x32_bf16 v[128:131], v[132:135], v[6:9], v[86:89]
	v_mfma_f32_16x16x32_bf16 v[132:135], v[132:135], v[14:17], v[102:105]
	s_waitcnt lgkmcnt(3)
	v_mfma_f32_16x16x32_bf16 v[102:105], v[136:139], v[2:5], v[74:77]
	v_mfma_f32_16x16x32_bf16 v[86:89], v[136:139], v[10:13], v[90:93]
	s_waitcnt lgkmcnt(2)
	v_mfma_f32_16x16x32_bf16 v[98:101], v[140:143], v[2:5], v[78:81]
	v_mfma_f32_16x16x32_bf16 v[82:85], v[140:143], v[10:13], v[94:97]
	s_waitcnt lgkmcnt(1)
	v_mfma_f32_16x16x32_bf16 v[94:97], v[176:179], v[2:5], v[120:123]
	v_mfma_f32_16x16x32_bf16 v[78:81], v[176:179], v[10:13], v[124:127]
	s_waitcnt lgkmcnt(0)
	v_mfma_f32_16x16x32_bf16 v[90:93], v[180:183], v[2:5], v[128:131]
	v_mfma_f32_16x16x32_bf16 v[74:77], v[180:183], v[10:13], v[132:135]
	s_setprio 0
	v_max3_f32 v120, v102, s96, v103
	v_max3_f32 v120, v120, v104, v105
	v_max3_f32 v120, v120, v98, v99
	v_max3_f32 v120, v120, v100, v101
	v_max3_f32 v120, v120, v94, v95
	v_max3_f32 v120, v120, v96, v97
	v_max3_f32 v120, v120, v90, v91
	v_max3_f32 v121, v120, v92, v93
	v_max3_f32 v120, v121, v86, v87
	v_max3_f32 v120, v120, v88, v89
	v_max3_f32 v120, v120, v82, v83
	v_max3_f32 v120, v120, v84, v85
	v_max3_f32 v120, v120, v78, v79
	v_max3_f32 v120, v120, v80, v81
	v_max3_f32 v120, v120, v74, v75
	v_max3_f32 v120, v120, v76, v77
	s_mov_b32 s0, 0x41000000
	v_cmp_lt_f32_e32 vcc, s0, v120
	s_cbranch_vccnz .LBB0_1482
	v_cmp_lt_f32_e32 vcc, s94, v120
	s_cbranch_vccz .LBB0_1463

.LBB0_1463:
	s_waitcnt vmcnt(2)
	s_cmp_lt_i32 s7, 0
	s_cbranch_scc1 .LBB0_1465
	ds_write_b128 v115, v[18:21]
	ds_write_b128 v116, v[22:25]

.LBB0_1470:
	s_cmp_lt_i32 s7, 0
	s_mov_b64 s[0:1], -1
	s_cbranch_scc1 .LBB0_1457
	s_max_i32 s0, s18, 0
	s_lshl_b32 s76, s0, 6
	v_lshl_add_u64 v[18:19], v[152:153], 0, s[76:77]
	v_mad_u64_u32 v[22:23], s[0:1], v18, s33, v[106:107]
	v_mad_i32_i24 v23, v19, s33, v23
	global_load_dwordx4 v[18:21], v[22:23], off offset:1024
	s_nop 0
	global_load_dwordx4 v[22:25], v[22:23], off offset:1152
	s_max_i32 s98, s9, 0
	s_lshr_b32 s98, s98, 3
	s_and_b32 s98, s98, 0x1ffffffc
	v_add_u32_e32 v244, s98, v157
	ds_read_b32 v242, v244 offset:16
	s_and_b32 s16, s7, 31
	v_lshrrev_b32_e32 v75, s7, v243
	v_and_b32_e32 v75, 1, v75
	v_bfe_u32 v74, v243, s16, 1
	v_cmp_eq_u32_e64 s[0:1], 1, v75
	v_cmp_ne_u32_e32 vcc, 0, v74
	s_cbranch_vccz .LBB0_1475
	ds_read_b128 v[120:123], v117
	ds_read_b128 v[124:127], v117 offset:2560
	ds_read_b128 v[128:131], v117 offset:5120
	ds_read_b128 v[132:135], v117 offset:7680
	ds_read_b128 v[136:139], v117 offset:64
	ds_read_b128 v[140:143], v117 offset:2624
	ds_read_b128 v[176:179], v117 offset:5184
	ds_read_b128 v[180:183], v117 offset:7744
	v_lshl_add_u32 v74, s7, 6, v111
	v_cvt_f32_i32_e32 v90, v74
	v_fma_f32 v74, v146, v90, -v109
	v_fma_f32 v90, v148, v90, -v110
	v_cndmask_b32_e64 v89, v173, v74, s[0:1]
	v_cndmask_b32_e64 v105, v173, v90, s[0:1]
	v_fma_f32 v74, v146, s77, v89
	v_fma_f32 v75, v146, s95, v89
	v_fma_f32 v76, v146, s4, v89
	v_fma_f32 v77, v146, s5, v89
	v_fma_f32 v78, v146, s86, v89
	v_fma_f32 v79, v146, s87, v89
	v_fma_f32 v80, v146, s84, v89
	v_fma_f32 v81, v146, s85, v89
	v_fma_f32 v82, v146, s88, v89
	v_fma_f32 v83, v146, s89, v89
	v_fma_f32 v84, v146, s90, v89
	v_fma_f32 v85, v146, s91, v89
	v_fma_f32 v86, v146, s72, v89
	v_fma_f32 v87, v146, s73, v89
	v_fma_f32 v88, v146, s74, v89
	v_fma_f32 v89, v146, s75, v89
	v_fma_f32 v90, v148, s77, v105
	v_fma_f32 v91, v148, s95, v105
	v_fma_f32 v92, v148, s4, v105
	v_fma_f32 v93, v148, s5, v105
	v_fma_f32 v94, v148, s86, v105
	v_fma_f32 v95, v148, s87, v105
	v_fma_f32 v96, v148, s84, v105
	v_fma_f32 v97, v148, s85, v105
	v_fma_f32 v98, v148, s88, v105
	v_fma_f32 v99, v148, s89, v105
	v_fma_f32 v100, v148, s90, v105
	v_fma_f32 v101, v148, s91, v105
	v_fma_f32 v102, v148, s72, v105
	v_fma_f32 v103, v148, s73, v105
	v_fma_f32 v104, v148, s74, v105
	v_fma_f32 v105, v148, s75, v105
	s_setprio 1
	s_waitcnt lgkmcnt(7)
	v_mfma_f32_16x16x32_bf16 v[74:77], v[120:123], v[6:9], v[74:77]
	v_mfma_f32_16x16x32_bf16 v[90:93], v[120:123], v[14:17], v[90:93]
	s_waitcnt lgkmcnt(6)
	v_mfma_f32_16x16x32_bf16 v[78:81], v[124:127], v[6:9], v[78:81]
	v_mfma_f32_16x16x32_bf16 v[94:97], v[124:127], v[14:17], v[94:97]
	s_waitcnt lgkmcnt(5)
	v_mfma_f32_16x16x32_bf16 v[120:123], v[128:131], v[6:9], v[82:85]
	v_mfma_f32_16x16x32_bf16 v[124:127], v[128:131], v[14:17], v[98:101]
	s_waitcnt lgkmcnt(4)
	v_mfma_f32_16x16x32_bf16 v[128:131], v[132:135], v[6:9], v[86:89]
	v_mfma_f32_16x16x32_bf16 v[132:135], v[132:135], v[14:17], v[102:105]
	s_waitcnt lgkmcnt(3)
	v_mfma_f32_16x16x32_bf16 v[102:105], v[136:139], v[2:5], v[74:77]
	v_mfma_f32_16x16x32_bf16 v[86:89], v[136:139], v[10:13], v[90:93]
	s_waitcnt lgkmcnt(2)
	v_mfma_f32_16x16x32_bf16 v[98:101], v[140:143], v[2:5], v[78:81]
	v_mfma_f32_16x16x32_bf16 v[82:85], v[140:143], v[10:13], v[94:97]
	s_waitcnt lgkmcnt(1)
	v_mfma_f32_16x16x32_bf16 v[94:97], v[176:179], v[2:5], v[120:123]
	v_mfma_f32_16x16x32_bf16 v[78:81], v[176:179], v[10:13], v[124:127]
	s_waitcnt lgkmcnt(0)
	v_mfma_f32_16x16x32_bf16 v[90:93], v[180:183], v[2:5], v[128:131]
	v_mfma_f32_16x16x32_bf16 v[74:77], v[180:183], v[10:13], v[132:135]
	s_setprio 0
	v_max3_f32 v120, v102, s96, v103
	v_max3_f32 v120, v120, v104, v105
	v_max3_f32 v120, v120, v98, v99
	v_max3_f32 v120, v120, v100, v101
	v_max3_f32 v120, v120, v94, v95
	v_max3_f32 v120, v120, v96, v97
	v_max3_f32 v120, v120, v90, v91
	v_max3_f32 v121, v120, v92, v93
	v_max3_f32 v120, v121, v86, v87
	v_max3_f32 v120, v120, v88, v89
	v_max3_f32 v120, v120, v82, v83
	v_max3_f32 v120, v120, v84, v85
	v_max3_f32 v120, v120, v78, v79
	v_max3_f32 v120, v120, v80, v81
	v_max3_f32 v120, v120, v74, v75
	v_max3_f32 v120, v120, v76, v77
	s_mov_b32 s0, 0x41000000
	v_cmp_lt_f32_e32 vcc, s0, v120
	s_cbranch_vccnz .LBB0_1483
	v_cmp_lt_f32_e32 vcc, s94, v120
	s_cbranch_vccz .LBB0_1475

.LBB0_1493:
	s_add_i32 s13, s12, 1
	s_max_i32 s0, s13, s15
	s_lshl_b32 s76, s0, 6
	v_lshl_add_u64 v[66:67], v[152:153], 0, s[76:77]
	v_mad_u64_u32 v[70:71], s[0:1], v66, s33, v[154:155]
	v_mad_i32_i24 v71, v67, s33, v71
	global_load_dwordx4 v[66:69], v[70:71], off offset:2048
	s_nop 0
	global_load_dwordx4 v[70:73], v[70:71], off offset:2176
	ds_read_b128 v[106:109], v1 offset:20480
	ds_read_b128 v[110:113], v1 offset:23040
	ds_read_b128 v[114:117], v1 offset:25600
	ds_read_b128 v[118:121], v1 offset:28160
	ds_read_b128 v[122:125], v1 offset:20544
	ds_read_b128 v[126:129], v1 offset:23104
	ds_read_b128 v[130:133], v1 offset:25664
	ds_read_b128 v[134:137], v1 offset:28224
	v_add_u32_e32 v74, 64, v164
	v_cvt_f32_i32_e32 v90, v74
	v_fma_f32 v89, v146, v90, -v176
	v_fma_f32 v105, v148, v90, -v177
	v_fma_f32 v74, v146, s77, v89
	v_fma_f32 v75, v146, s95, v89
	v_fma_f32 v76, v146, s4, v89
	v_fma_f32 v77, v146, s5, v89
	v_fma_f32 v78, v146, s86, v89
	v_fma_f32 v79, v146, s87, v89
	v_fma_f32 v80, v146, s84, v89
	v_fma_f32 v81, v146, s85, v89
	v_fma_f32 v82, v146, s88, v89
	v_fma_f32 v83, v146, s89, v89
	v_fma_f32 v84, v146, s90, v89
	v_fma_f32 v85, v146, s91, v89
	v_fma_f32 v86, v146, s72, v89
	v_fma_f32 v87, v146, s73, v89
	v_fma_f32 v88, v146, s74, v89
	v_fma_f32 v89, v146, s75, v89
	v_fma_f32 v90, v148, s77, v105
	v_fma_f32 v91, v148, s95, v105
	v_fma_f32 v92, v148, s4, v105
	v_fma_f32 v93, v148, s5, v105
	v_fma_f32 v94, v148, s86, v105
	v_fma_f32 v95, v148, s87, v105
	v_fma_f32 v96, v148, s84, v105
	v_fma_f32 v97, v148, s85, v105
	v_fma_f32 v98, v148, s88, v105
	v_fma_f32 v99, v148, s89, v105
	v_fma_f32 v100, v148, s90, v105
	v_fma_f32 v101, v148, s91, v105
	v_fma_f32 v102, v148, s72, v105
	v_fma_f32 v103, v148, s73, v105
	v_fma_f32 v104, v148, s74, v105
	v_fma_f32 v105, v148, s75, v105
	s_setprio 1
	s_waitcnt lgkmcnt(7)
	v_mfma_f32_16x16x32_bf16 v[74:77], v[106:109], v[6:9], v[74:77]
	v_mfma_f32_16x16x32_bf16 v[90:93], v[106:109], v[14:17], v[90:93]
	s_waitcnt lgkmcnt(6)
	v_mfma_f32_16x16x32_bf16 v[78:81], v[110:113], v[6:9], v[78:81]
	v_mfma_f32_16x16x32_bf16 v[94:97], v[110:113], v[14:17], v[94:97]
	s_waitcnt lgkmcnt(5)
	v_mfma_f32_16x16x32_bf16 v[106:109], v[114:117], v[6:9], v[82:85]
	v_mfma_f32_16x16x32_bf16 v[110:113], v[114:117], v[14:17], v[98:101]
	s_waitcnt lgkmcnt(4)
	v_mfma_f32_16x16x32_bf16 v[114:117], v[118:121], v[6:9], v[86:89]
	v_mfma_f32_16x16x32_bf16 v[118:121], v[118:121], v[14:17], v[102:105]
	s_waitcnt lgkmcnt(3)
	v_mfma_f32_16x16x32_bf16 v[102:105], v[122:125], v[2:5], v[74:77]
	v_mfma_f32_16x16x32_bf16 v[86:89], v[122:125], v[10:13], v[90:93]
	s_waitcnt lgkmcnt(2)
	v_mfma_f32_16x16x32_bf16 v[98:101], v[126:129], v[2:5], v[78:81]
	v_mfma_f32_16x16x32_bf16 v[82:85], v[126:129], v[10:13], v[94:97]
	s_waitcnt lgkmcnt(1)
	v_mfma_f32_16x16x32_bf16 v[94:97], v[130:133], v[2:5], v[106:109]
	v_mfma_f32_16x16x32_bf16 v[78:81], v[130:133], v[10:13], v[110:113]
	s_waitcnt lgkmcnt(0)
	v_mfma_f32_16x16x32_bf16 v[90:93], v[134:137], v[2:5], v[114:117]
	v_mfma_f32_16x16x32_bf16 v[74:77], v[134:137], v[10:13], v[118:121]
	s_setprio 0
	v_max3_f32 v106, v102, s96, v103
	v_max3_f32 v106, v106, v104, v105
	v_max3_f32 v106, v106, v98, v99
	v_max3_f32 v106, v106, v100, v101
	v_max3_f32 v106, v106, v94, v95
	v_max3_f32 v106, v106, v96, v97
	v_max3_f32 v106, v106, v90, v91
	v_max3_f32 v107, v106, v92, v93
	v_max3_f32 v106, v107, v86, v87
	v_max3_f32 v106, v106, v88, v89
	v_max3_f32 v106, v106, v82, v83
	v_max3_f32 v106, v106, v84, v85
	v_max3_f32 v106, v106, v78, v79
	v_max3_f32 v106, v106, v80, v81
	v_max3_f32 v106, v106, v74, v75
	v_max3_f32 v106, v106, v76, v77
	s_mov_b32 s0, 0x41000000
	v_cmp_lt_f32_e32 vcc, s0, v106
	s_cbranch_vccnz .LBB0_1506
	v_mov_b32_e32 v178, v177
	v_mov_b32_e32 v179, v176
	v_cmp_lt_f32_e32 vcc, s94, v106
	s_cbranch_vccz .LBB0_1507

.LBB0_1497:
	s_waitcnt vmcnt(2)
	s_mov_b64 s[0:1], -1
	s_cmp_lt_i32 s16, s17
	v_readfirstlane_b32 s18, v0
	s_mov_b64 s[8:9], -1
	s_waitcnt lgkmcnt(0)
	s_barrier
	s_cbranch_scc1 .LBB0_1504
	s_max_i32 s0, s12, s15
	s_lshl_b32 s76, s0, 6
	s_waitcnt vmcnt(3)
	v_lshl_add_u64 v[18:19], v[152:153], 0, s[76:77]
	s_waitcnt vmcnt(2)
	v_mad_u64_u32 v[22:23], s[0:1], v18, s33, v[154:155]
	v_mad_i32_i24 v23, v19, s33, v23
	global_load_dwordx4 v[18:21], v[22:23], off offset:2048
	s_nop 0
	global_load_dwordx4 v[22:25], v[22:23], off offset:2176
	ds_read_b128 v[58:61], v1
	ds_read_b128 v[62:65], v1 offset:2560
	ds_read_b128 v[114:117], v1 offset:5120
	ds_read_b128 v[118:121], v1 offset:7680
	ds_read_b128 v[122:125], v1 offset:64
	ds_read_b128 v[130:133], v1 offset:2624
	ds_read_b128 v[180:183], v1 offset:5184
	ds_read_b128 v[184:187], v1 offset:7744
	v_cvt_f32_i32_e32 v42, v164
	v_fma_f32 v41, v146, v42, -v179
	v_fma_f32 v57, v148, v42, -v178
	v_fma_f32 v26, v146, s77, v41
	v_fma_f32 v27, v146, s95, v41
	v_fma_f32 v28, v146, s4, v41
	v_fma_f32 v29, v146, s5, v41
	v_fma_f32 v30, v146, s86, v41
	v_fma_f32 v31, v146, s87, v41
	v_fma_f32 v32, v146, s84, v41
	v_fma_f32 v33, v146, s85, v41
	v_fma_f32 v34, v146, s88, v41
	v_fma_f32 v35, v146, s89, v41
	v_fma_f32 v36, v146, s90, v41
	v_fma_f32 v37, v146, s91, v41
	v_fma_f32 v38, v146, s72, v41
	v_fma_f32 v39, v146, s73, v41
	v_fma_f32 v40, v146, s74, v41
	v_fma_f32 v41, v146, s75, v41
	v_fma_f32 v42, v148, s77, v57
	v_fma_f32 v43, v148, s95, v57
	v_fma_f32 v44, v148, s4, v57
	v_fma_f32 v45, v148, s5, v57
	v_fma_f32 v46, v148, s86, v57
	v_fma_f32 v47, v148, s87, v57
	v_fma_f32 v48, v148, s84, v57
	v_fma_f32 v49, v148, s85, v57
	v_fma_f32 v50, v148, s88, v57
	v_fma_f32 v51, v148, s89, v57
	v_fma_f32 v52, v148, s90, v57
	v_fma_f32 v53, v148, s91, v57
	v_fma_f32 v54, v148, s72, v57
	v_fma_f32 v55, v148, s73, v57
	v_fma_f32 v56, v148, s74, v57
	v_fma_f32 v57, v148, s75, v57
	s_setprio 1
	s_waitcnt lgkmcnt(7)
	v_mfma_f32_16x16x32_bf16 v[26:29], v[58:61], v[6:9], v[26:29]
	v_mfma_f32_16x16x32_bf16 v[42:45], v[58:61], v[14:17], v[42:45]
	s_waitcnt lgkmcnt(6)
	v_mfma_f32_16x16x32_bf16 v[30:33], v[62:65], v[6:9], v[30:33]
	v_mfma_f32_16x16x32_bf16 v[46:49], v[62:65], v[14:17], v[46:49]
	s_waitcnt lgkmcnt(5)
	v_mfma_f32_16x16x32_bf16 v[34:37], v[114:117], v[6:9], v[34:37]
	v_mfma_f32_16x16x32_bf16 v[50:53], v[114:117], v[14:17], v[50:53]
	s_waitcnt lgkmcnt(4)
	v_mfma_f32_16x16x32_bf16 v[38:41], v[118:121], v[6:9], v[38:41]
	v_mfma_f32_16x16x32_bf16 v[54:57], v[118:121], v[14:17], v[54:57]
	s_waitcnt lgkmcnt(3)
	v_mfma_f32_16x16x32_bf16 v[142:145], v[122:125], v[2:5], v[26:29]
	v_mfma_f32_16x16x32_bf16 v[126:129], v[122:125], v[10:13], v[42:45]
	s_waitcnt lgkmcnt(2)
	v_mfma_f32_16x16x32_bf16 v[138:141], v[130:133], v[2:5], v[30:33]
	v_mfma_f32_16x16x32_bf16 v[122:125], v[130:133], v[10:13], v[46:49]
	s_waitcnt lgkmcnt(1)
	v_mfma_f32_16x16x32_bf16 v[134:137], v[180:183], v[2:5], v[34:37]
	v_mfma_f32_16x16x32_bf16 v[118:121], v[180:183], v[10:13], v[50:53]
	s_waitcnt lgkmcnt(0)
	v_mfma_f32_16x16x32_bf16 v[130:133], v[184:187], v[2:5], v[38:41]
	v_mfma_f32_16x16x32_bf16 v[114:117], v[184:187], v[10:13], v[54:57]
	s_setprio 0
	v_max3_f32 v26, v142, s96, v143
	v_max3_f32 v26, v26, v144, v145
	v_max3_f32 v26, v26, v138, v139
	v_max3_f32 v26, v26, v140, v141
	v_max3_f32 v26, v26, v134, v135
	v_max3_f32 v26, v26, v136, v137
	v_max3_f32 v26, v26, v130, v131
	v_max3_f32 v181, v26, v132, v133
	v_max3_f32 v26, v181, v126, v127
	v_max3_f32 v26, v26, v128, v129
	v_max3_f32 v26, v26, v122, v123
	v_max3_f32 v26, v26, v124, v125
	v_max3_f32 v26, v26, v118, v119
	v_max3_f32 v26, v26, v120, v121
	v_max3_f32 v26, v26, v114, v115
	v_max3_f32 v180, v26, v116, v117
	s_mov_b32 s0, 0x41000000
	v_mov_b64_e32 v[62:63], v[94:95]
	v_mov_b64_e32 v[50:51], v[102:103]
	v_mov_b64_e32 v[34:35], v[74:75]
	v_mov_b64_e32 v[54:55], v[78:79]
	v_mov_b64_e32 v[38:39], v[82:83]
	v_mov_b64_e32 v[58:59], v[86:87]
	v_mov_b64_e32 v[26:27], v[90:91]
	v_mov_b64_e32 v[42:43], v[98:99]
	v_mov_b64_e32 v[30:31], v[106:107]
	v_mov_b64_e32 v[46:47], v[110:111]
	v_cmp_lt_f32_e32 vcc, s0, v180
	v_mov_b64_e32 v[64:65], v[96:97]
	v_mov_b64_e32 v[52:53], v[104:105]
	v_mov_b32_e32 v177, v178
	v_mov_b32_e32 v176, v179
	v_mov_b64_e32 v[36:37], v[76:77]
	v_mov_b64_e32 v[56:57], v[80:81]
	v_mov_b64_e32 v[40:41], v[84:85]
	v_mov_b64_e32 v[60:61], v[88:89]
	v_mov_b64_e32 v[28:29], v[92:93]
	v_mov_b64_e32 v[44:45], v[100:101]
	v_mov_b64_e32 v[32:33], v[108:109]
	v_mov_b64_e32 v[48:49], v[112:113]
	s_cbranch_vccnz .LBB0_1508
	v_cmp_lt_f32_e32 vcc, s94, v180
	s_cbranch_vccz .LBB0_1501

	.amdhsa_kernel _Z6mk_fwd4Args
		.amdhsa_group_segment_fixed_size 0
		.amdhsa_private_segment_fixed_size 0
		.amdhsa_kernarg_size 536
		.amdhsa_user_sgpr_count 2
		.amdhsa_user_sgpr_dispatch_ptr 0
		.amdhsa_user_sgpr_queue_ptr 0
		.amdhsa_user_sgpr_kernarg_segment_ptr 1
		.amdhsa_user_sgpr_dispatch_id 0
		.amdhsa_user_sgpr_kernarg_preload_length 0
		.amdhsa_user_sgpr_kernarg_preload_offset 0
		.amdhsa_user_sgpr_private_segment_size 0
		.amdhsa_uses_dynamic_stack 0
		.amdhsa_enable_private_segment 0
		.amdhsa_system_sgpr_workgroup_id_x 1
		.amdhsa_system_sgpr_workgroup_id_y 0
		.amdhsa_system_sgpr_workgroup_id_z 0
		.amdhsa_system_sgpr_workgroup_info 0
		.amdhsa_system_vgpr_workitem_id 0
		.amdhsa_next_free_vgpr 248
		.amdhsa_next_free_sgpr 100
		.amdhsa_accum_offset 248
		.amdhsa_reserve_vcc 1
		.amdhsa_float_round_mode_32 0
		.amdhsa_float_round_mode_16_64 0
		.amdhsa_float_denorm_mode_32 3
		.amdhsa_float_denorm_mode_16_64 3
		.amdhsa_dx10_clamp 1
		.amdhsa_ieee_mode 1
		.amdhsa_fp16_overflow 0
		.amdhsa_tg_split 0
		.amdhsa_exception_fp_ieee_invalid_op 0
		.amdhsa_exception_fp_denorm_src 0
		.amdhsa_exception_fp_ieee_div_zero 0
		.amdhsa_exception_fp_ieee_overflow 0
		.amdhsa_exception_fp_ieee_underflow 0
		.amdhsa_exception_fp_ieee_inexact 0
		.amdhsa_exception_int_div_zero 0
	.end_amdhsa_kernel

amdhsa.kernels:
  - .agpr_count:     0
    .args:
      - .offset:         0
        .size:           280
        .value_kind:     by_value
      - .offset:         280
        .size:           4
        .value_kind:     hidden_block_count_x
      - .offset:         284
        .size:           4
        .value_kind:     hidden_block_count_y
      - .offset:         288
        .size:           4
        .value_kind:     hidden_block_count_z
      - .offset:         292
        .size:           2
        .value_kind:     hidden_group_size_x
      - .offset:         294
        .size:           2
        .value_kind:     hidden_group_size_y
      - .offset:         296
        .size:           2
        .value_kind:     hidden_group_size_z
      - .offset:         298
        .size:           2
        .value_kind:     hidden_remainder_x
      - .offset:         300
        .size:           2
        .value_kind:     hidden_remainder_y
      - .offset:         302
        .size:           2
        .value_kind:     hidden_remainder_z
      - .offset:         320
        .size:           8
        .value_kind:     hidden_global_offset_x
      - .offset:         328
        .size:           8
        .value_kind:     hidden_global_offset_y
      - .offset:         336
        .size:           8
        .value_kind:     hidden_global_offset_z
      - .offset:         344
        .size:           2
        .value_kind:     hidden_grid_dims
      - .offset:         400
        .size:           4
        .value_kind:     hidden_dynamic_lds_size
    .group_segment_fixed_size: 0
    .kernarg_segment_align: 8
    .kernarg_segment_size: 536
    .language:       OpenCL C
    .language_version:
      - 2
      - 0
    .max_flat_workgroup_size: 512
    .name:           _Z6mk_fwd4Args
    .private_segment_fixed_size: 0
    .sgpr_count:     106
    .sgpr_spill_count: 115
    .symbol:         _Z6mk_fwd4Args.kd
    .uniform_work_group_size: 1
    .uses_dynamic_stack: false
    .vgpr_count:     248
    .vgpr_spill_count: 0
    .wavefront_size: 64
